# P3 attention: P operand kept in per-lane key order (no permlane swaps), V rows stored in matching order
# baseline (speedup 1.0000x reference)
.LBB0_432:
	s_ashr_i32 s69, s59, 6
	s_lshl_b32 s3, s59, 8
	s_lshl_b32 s2, s69, 11
	s_and_b32 s3, s3, 0x700
	s_bfe_u32 s6, s59, 0x10005
	s_or_b32 s26, s2, s3
	s_lshl_b32 s3, s59, 4
	s_ashr_i32 s27, s26, 31
	s_lshl_b32 s2, s6, 9
	s_and_b32 s3, s3, 0x180
	s_lshl_b32 s68, s6, 8
	s_or_b32 s63, s2, s3
	s_lshl_b64 s[2:3], s[26:27], 11
	s_add_u32 s2, s22, s2
	s_addc_u32 s3, s23, s3
	s_lshl_b32 s7, s63, 1
	s_add_u32 s8, s2, s7
	s_mul_i32 s2, s69, 0x1200
	s_addc_u32 s9, s3, 0
	s_mul_hi_i32 s3, s69, 0x1200
	s_or_b32 s2, s2, s6
	v_mov_b32_e32 v68, v208
	s_lshl_b64 s[6:7], s[2:3], 8
	s_add_u32 s2, s24, s6
	v_ashrrev_i32_e32 v16, 4, v68
	v_lshlrev_b32_e32 v22, 3, v68
	v_add_u32_e32 v18, 32, v16
	s_addc_u32 s3, s25, s7
	v_and_b32_e32 v0, 0x78, v22
	v_ashrrev_i32_e32 v17, 31, v16
	v_ashrrev_i32_e32 v19, 31, v18
	s_add_u32 s6, s1, s6
	v_lshlrev_b32_e32 v23, 1, v0
	v_lshlrev_b64 v[48:49], 9, v[16:17]
	v_lshlrev_b64 v[8:9], 9, v[18:19]
	s_addc_u32 s7, s54, s7
	v_or_b32_e32 v50, v48, v23
	v_mov_b32_e32 v51, v49
	v_or_b32_e32 v8, v8, v23
	v_ashrrev_i32_e32 v155, 6, v68
	v_lshl_add_u64 v[0:1], s[6:7], 0, v[50:51]
	v_lshl_add_u64 v[4:5], s[6:7], 0, v[8:9]
	v_lshl_add_u64 v[10:11], s[2:3], 0, v[50:51]
	v_lshl_add_u64 v[12:13], s[2:3], 0, v[8:9]
	v_and_b32_e32 v154, 31, v68
	v_lshlrev_b32_e32 v130, 5, v155
	global_load_dwordx4 v[0:3], v[0:1], off
	s_nop 0
	global_load_dwordx4 v[4:7], v[4:5], off
	s_nop 0
	global_load_dwordx4 v[8:11], v[10:11], off
	s_nop 0
	global_load_dwordx4 v[12:15], v[12:13], off
	v_or_b32_e32 v20, v130, v154
	v_ashrrev_i32_e32 v21, 31, v20
	v_bfe_u32 v153, v68, 5, 1
	v_lshlrev_b64 v[20:21], 11, v[20:21]
	v_lshl_add_u64 v[20:21], s[8:9], 0, v[20:21]
	v_lshlrev_b32_e32 v128, 4, v153
	v_lshl_add_u64 v[20:21], v[20:21], 0, v[128:129]
	global_load_dwordx4 v[124:127], v[20:21], off
	global_load_dwordx4 v[120:123], v[20:21], off offset:32
	global_load_dwordx4 v[112:115], v[20:21], off offset:64
	global_load_dwordx4 v[116:119], v[20:21], off offset:96
	global_load_dwordx4 v[108:111], v[20:21], off offset:128
	global_load_dwordx4 v[104:107], v[20:21], off offset:160
	global_load_dwordx4 v[100:103], v[20:21], off offset:192
	global_load_dwordx4 v[96:99], v[20:21], off offset:224
	v_and_b32_e32 v19, 0xfffff0, v16
	v_lshlrev_b32_e32 v24, 1, v16
	v_lshrrev_b32_e32 v25, 1, v16
	v_and_b32_e32 v26, 3, v16
	v_and_or_b32 v19, v16, 8, v19
	v_and_or_b32 v24, v16, 4, v26
	v_and_b32_e32 v25, 0xfffff0, v18
	v_and_or_b32 v25, v18, 8, v25
	v_lshlrev_b32_e32 v26, 1, v18
	v_and_b32_e32 v17, 0x70, v68
	v_bfe_u32 v22, v22, 5, 2
	v_lshlrev_b32_e32 v16, 8, v16
	v_lshlrev_b32_e32 v18, 8, v18
	v_lshrrev_b32_e32 v19, 1, v19
	v_lshlrev_b32_e32 v156, 4, v68
	v_bitop3_b32 v162, v23, v16, v17 bitop3:0xde
	v_bitop3_b32 v163, v23, v18, v17 bitop3:0xde
	v_or_b32_e32 v16, v19, v22
	v_lshrrev_b32_e32 v17, 1, v25
	v_lshlrev_b32_e32 v24, 6, v24
	v_and_b32_e32 v27, 48, v23
	v_lshlrev_b32_e32 v16, 9, v16
	v_or_b32_e32 v17, v17, v22
	v_lshlrev_b32_e32 v60, 8, v154
	v_and_b32_e32 v61, 0x70, v156
	v_or3_b32 v164, v16, v24, v27
	v_lshlrev_b32_e32 v16, 9, v17
	v_bitop3_b32 v166, v128, v60, v61 bitop3:0xde
	v_or3_b32 v165, v16, v24, v27
	s_waitcnt vmcnt(0)
	v_and_b32_e32 v62, 0x3fffffc0, v68
	v_and_b32_e32 v157, 63, v68
	v_lshlrev_b32_e32 v63, 1, v68
	v_lshl_add_u32 v131, v62, 2, v150
	v_lshlrev_b32_e32 v62, 3, v157
	v_lshl_or_b32 v158, v154, 2, v131
	s_waitcnt vmcnt(11)
	ds_write_b128 v164, v[0:3]
	s_waitcnt vmcnt(10)
	ds_write_b128 v165, v[4:7]
	s_waitcnt vmcnt(9)
	ds_write_b128 v162, v[8:11] offset:32768
	s_waitcnt vmcnt(8)
	ds_write_b128 v163, v[12:15] offset:32768
	s_waitcnt lgkmcnt(0)
	s_barrier
	ds_read_b128 v[0:3], v166 offset:32768
	ds_read_b128 v[4:7], v166 offset:40960
	s_waitcnt vmcnt(7) lgkmcnt(1)
	v_mfma_f32_32x32x16_bf16 v[32:47], v[0:3], v[124:127], 0
	v_or_b32_e32 v0, 32, v128
	v_bitop3_b32 v167, v0, v60, v61 bitop3:0xde
	v_mov_b32_e32 v159, 0
	s_waitcnt lgkmcnt(0)
	v_mfma_f32_32x32x16_bf16 v[16:31], v[4:7], v[124:127], 0
	ds_read_b128 v[0:3], v167 offset:32768
	ds_read_b128 v[4:7], v167 offset:40960
	s_waitcnt vmcnt(6) lgkmcnt(1)
	v_mfma_f32_32x32x16_bf16 v[32:47], v[0:3], v[120:123], v[32:47]
	v_or_b32_e32 v0, 64, v128
	v_bitop3_b32 v168, v0, v60, v61 bitop3:0xde
	s_waitcnt lgkmcnt(0)
	v_mfma_f32_32x32x16_bf16 v[16:31], v[4:7], v[120:123], v[16:31]
	ds_read_b128 v[0:3], v168 offset:32768
	ds_read_b128 v[4:7], v168 offset:40960
	s_waitcnt vmcnt(5) lgkmcnt(1)
	v_mfma_f32_32x32x16_bf16 v[32:47], v[0:3], v[112:115], v[32:47]
	v_or_b32_e32 v0, 0x60, v128
	v_bitop3_b32 v169, v0, v60, v61 bitop3:0xde
	s_waitcnt lgkmcnt(0)
	v_mfma_f32_32x32x16_bf16 v[16:31], v[4:7], v[112:115], v[16:31]
	ds_read_b128 v[0:3], v169 offset:32768
	ds_read_b128 v[4:7], v169 offset:40960
	s_waitcnt vmcnt(4) lgkmcnt(1)
	v_mfma_f32_32x32x16_bf16 v[32:47], v[0:3], v[116:119], v[32:47]
	v_or_b32_e32 v0, 0x80, v128
	v_bitop3_b32 v170, v0, v60, v61 bitop3:0xde
	s_waitcnt lgkmcnt(0)
	v_mfma_f32_32x32x16_bf16 v[16:31], v[4:7], v[116:119], v[16:31]
	ds_read_b128 v[0:3], v170 offset:32768
	ds_read_b128 v[4:7], v170 offset:40960
	s_waitcnt vmcnt(3) lgkmcnt(1)
	v_mfma_f32_32x32x16_bf16 v[32:47], v[0:3], v[108:111], v[32:47]
	v_or_b32_e32 v0, 0xa0, v128
	v_bitop3_b32 v171, v0, v60, v61 bitop3:0xde
	s_waitcnt lgkmcnt(0)
	v_mfma_f32_32x32x16_bf16 v[16:31], v[4:7], v[108:111], v[16:31]
	ds_read_b128 v[0:3], v171 offset:32768
	ds_read_b128 v[4:7], v171 offset:40960
	s_waitcnt vmcnt(2) lgkmcnt(1)
	v_mfma_f32_32x32x16_bf16 v[32:47], v[0:3], v[104:107], v[32:47]
	v_or_b32_e32 v0, 0xc0, v128
	v_bitop3_b32 v172, v0, v60, v61 bitop3:0xde
	ds_read_b128 v[52:55], v172 offset:32768
	ds_read_b128 v[56:59], v172 offset:40960
	s_waitcnt lgkmcnt(2)
	v_mfma_f32_32x32x16_bf16 v[16:31], v[4:7], v[104:107], v[16:31]
	v_mov_b64_e32 v[0:1], s[36:37]
	v_mov_b64_e32 v[14:15], s[50:51]
	v_mov_b64_e32 v[2:3], s[38:39]
	v_mov_b64_e32 v[4:5], s[40:41]
	v_mov_b64_e32 v[6:7], s[42:43]
	v_mov_b64_e32 v[8:9], s[44:45]
	v_mov_b64_e32 v[10:11], s[46:47]
	s_waitcnt vmcnt(1) lgkmcnt(1)
	v_mfma_f32_32x32x16_bf16 v[32:47], v[52:55], v[100:103], v[32:47]
	v_or_b32_e32 v52, 0xe0, v128
	v_bitop3_b32 v173, v52, v60, v61 bitop3:0xde
	ds_read_b128 v[52:55], v173 offset:32768
	v_lshl_add_u64 v[60:61], v[50:51], 0, s[16:17]
	v_lshl_add_u64 v[50:51], v[50:51], 0, s[18:19]
	v_lshl_add_u64 v[64:65], s[2:3], 0, v[50:51]
	v_mov_b64_e32 v[12:13], s[48:49]
	s_waitcnt lgkmcnt(1)
	v_mfma_f32_32x32x16_bf16 v[16:31], v[56:59], v[100:103], v[16:31]
	v_and_b32_e32 v56, 0xc0, v156
	v_and_b32_e32 v57, 32, v63
	v_and_or_b32 v56, v62, 24, v56
	v_and_b32_e32 v58, 0x100, v62
	v_or3_b32 v161, v56, v57, v58
	ds_read_b128 v[56:59], v173 offset:40960
	v_or_b32_e32 v160, 0x4000, v161
	s_waitcnt vmcnt(0) lgkmcnt(1)
	v_mfma_f32_32x32x16_bf16 v[32:47], v[52:55], v[96:99], v[32:47]
	v_lshl_add_u64 v[54:55], s[2:3], 0, v[60:61]
	v_lshl_add_u64 v[52:53], s[6:7], 0, v[60:61]
	v_lshl_add_u64 v[60:61], s[6:7], 0, v[50:51]
	global_load_dwordx4 v[50:53], v[52:53], off
	s_nop 0
	global_load_dwordx4 v[60:63], v[60:61], off
	v_cmp_gt_u32_e64 s[6:7], 32, v157
	s_waitcnt lgkmcnt(0)
	v_mfma_f32_32x32x16_bf16 v[16:31], v[56:59], v[96:99], v[16:31]
	global_load_dwordx4 v[54:57], v[54:55], off
	s_nop 0
	global_load_dwordx4 v[64:67], v[64:65], off
	v_max_f32_e32 v58, v33, v33
	v_max_f32_e32 v59, v32, v32
	v_max_f32_e32 v58, v59, v58
	v_max3_f32 v58, v58, v34, v35
	v_max3_f32 v58, v58, v36, v37
	v_max3_f32 v58, v58, v38, v39
	v_max3_f32 v58, v58, v40, v41
	v_max3_f32 v58, v58, v42, v43
	v_max3_f32 v58, v58, v44, v45
	v_max3_f32 v58, v58, v46, v47
	v_max3_f32 v58, v58, v16, v17
	v_max3_f32 v58, v58, v18, v19
	v_max3_f32 v58, v58, v20, v21
	v_max3_f32 v58, v58, v22, v23
	v_max3_f32 v58, v58, v24, v25
	v_max3_f32 v58, v58, v26, v27
	v_max3_f32 v58, v58, v28, v29
	v_max3_f32 v58, v58, v30, v31
	v_mov_b32_e32 v59, v58
	s_nop 1
	v_permlane32_swap_b32_e32 v58, v59
	v_max_f32_e32 v59, v59, v59
	v_max_f32_e32 v58, v58, v58
	v_max_f32_e32 v58, v58, v59
	v_add_f32_e32 v59, 0x7149f2ca, v58
	v_max_f32_e32 v58, 0xf149f2ca, v58
	v_cmp_ge_f32_e32 vcc, s15, v59
	v_sub_f32_e32 v59, 0xf149f2ca, v58
	v_mul_f32_e32 v59, 0x3e0293ee, v59
	v_exp_f32_e32 v59, v59
	s_cmp_eq_u64 vcc, exec
	s_cselect_b64 vcc, -1, 0
	v_cndmask_b32_e32 v175, v58, v151, vcc
	v_mul_f32_e32 v58, 0xbe0293ee, v175
	v_cndmask_b32_e64 v174, v59, 1.0, vcc
	v_mov_b32_e32 v59, v58
	v_fmac_f32_e32 v59, 0x3e0293ee, v47
	v_fmamk_f32 v32, v32, 0x3e0293ee, v58
	v_fmamk_f32 v33, v33, 0x3e0293ee, v58
	v_fmamk_f32 v34, v34, 0x3e0293ee, v58
	v_fmamk_f32 v35, v35, 0x3e0293ee, v58
	v_fmamk_f32 v36, v36, 0x3e0293ee, v58
	v_fmamk_f32 v37, v37, 0x3e0293ee, v58
	v_fmamk_f32 v38, v38, 0x3e0293ee, v58
	v_fmamk_f32 v39, v39, 0x3e0293ee, v58
	v_fmamk_f32 v40, v40, 0x3e0293ee, v58
	v_fmamk_f32 v41, v41, 0x3e0293ee, v58
	v_fmamk_f32 v42, v42, 0x3e0293ee, v58
	v_fmamk_f32 v43, v43, 0x3e0293ee, v58
	v_fmamk_f32 v44, v44, 0x3e0293ee, v58
	v_fmamk_f32 v45, v45, 0x3e0293ee, v58
	v_fmamk_f32 v46, v46, 0x3e0293ee, v58
	v_pk_fma_f32 v[140:141], v[18:19], s[14:15], v[58:59] op_sel_hi:[1,0,0]
	v_and_b32_e32 v18, 15, v68
	v_pk_fma_f32 v[142:143], v[16:17], s[14:15], v[58:59] op_sel_hi:[1,0,0]
	v_exp_f32_e32 v190, v32
	v_exp_f32_e32 v191, v33
	v_exp_f32_e32 v192, v34
	v_exp_f32_e32 v193, v35
	v_exp_f32_e32 v194, v36
	v_exp_f32_e32 v196, v37
	v_exp_f32_e32 v195, v38
	v_exp_f32_e32 v197, v39
	v_exp_f32_e32 v182, v40
	v_exp_f32_e32 v183, v41
	v_exp_f32_e32 v184, v42
	v_exp_f32_e32 v186, v43
	v_exp_f32_e32 v185, v44
	v_exp_f32_e32 v187, v45
	v_exp_f32_e32 v188, v46
	v_exp_f32_e32 v189, v59
	v_mad_i64_i32 v[16:17], s[2:3], s69, v152, v[48:49]
	v_lshlrev_b32_e32 v18, 4, v18
	s_waitcnt vmcnt(0)
	v_or3_b32 v16, v16, s68, v18
	v_pk_fma_f32 v[144:145], v[30:31], s[14:15], v[58:59] op_sel_hi:[1,0,0]
	v_pk_fma_f32 v[146:147], v[28:29], s[14:15], v[58:59] op_sel_hi:[1,0,0]
	v_pk_fma_f32 v[148:149], v[26:27], s[14:15], v[58:59] op_sel_hi:[1,0,0]
	v_pk_fma_f32 v[134:135], v[24:25], s[14:15], v[58:59] op_sel_hi:[1,0,0]
	v_pk_fma_f32 v[136:137], v[22:23], s[14:15], v[58:59] op_sel_hi:[1,0,0]
	v_pk_fma_f32 v[138:139], v[20:21], s[14:15], v[58:59] op_sel_hi:[1,0,0]
	s_waitcnt vmcnt(3)
	ds_write_b128 v164, v[50:53] offset:16384
	s_waitcnt vmcnt(2)
	ds_write_b128 v165, v[60:63] offset:16384
	s_waitcnt vmcnt(1)
	ds_write_b128 v162, v[54:57] offset:49152
	s_waitcnt vmcnt(0)
	ds_write_b128 v163, v[64:67] offset:49152
	v_lshl_add_u64 v[132:133], s[12:13], 0, v[16:17]
	v_mov_b64_e32 v[62:63], v[14:15]
	v_mov_b64_e32 v[46:47], v[14:15]
	v_mov_b64_e32 v[30:31], v[14:15]
	s_mov_b32 s68, -1
	v_mov_b64_e32 v[60:61], v[12:13]
	v_mov_b64_e32 v[58:59], v[10:11]
	v_mov_b64_e32 v[56:57], v[8:9]
	v_mov_b64_e32 v[54:55], v[6:7]
	v_mov_b64_e32 v[52:53], v[4:5]
	v_mov_b64_e32 v[50:51], v[2:3]
	v_mov_b64_e32 v[48:49], v[0:1]
	v_mov_b64_e32 v[44:45], v[12:13]
	v_mov_b64_e32 v[42:43], v[10:11]
	v_mov_b64_e32 v[40:41], v[8:9]
	v_mov_b64_e32 v[38:39], v[6:7]
	v_mov_b64_e32 v[36:37], v[4:5]
	v_mov_b64_e32 v[34:35], v[2:3]
	v_mov_b64_e32 v[32:33], v[0:1]
	v_mov_b64_e32 v[28:29], v[12:13]
	v_mov_b64_e32 v[26:27], v[10:11]
	v_mov_b64_e32 v[24:25], v[8:9]
	v_mov_b64_e32 v[22:23], v[6:7]
	v_mov_b64_e32 v[20:21], v[4:5]
	v_mov_b64_e32 v[18:19], v[2:3]
	v_mov_b64_e32 v[16:17], v[0:1]
	s_waitcnt lgkmcnt(0)
	s_barrier
	v_readfirstlane_b32 s28, v132
	v_readfirstlane_b32 s29, v133
	s_nop 1
	v_subrev_u32_e32 v132, s28, v132
	v_add_u32_e32 v133, 0x4000, v132
	s_sub_u32 s30, s28, 0x120c000
	s_subb_u32 s31, s29, 0
	s_sub_u32 s28, s28, 0xc000
	s_subb_u32 s29, s29, 0
.LBB0_433:
	ds_read_b128 v[64:67], v166 offset:49152
	ds_read_b128 v[68:71], v166 offset:57344
	ds_read_b128 v[176:179], v167 offset:49152
	ds_read_b128 v[198:201], v167 offset:57344
	ds_read_b128 v[202:205], v168 offset:49152
	ds_read_b128 v[210:213], v168 offset:57344
	v_exp_f32_e32 v142, v142
	v_exp_f32_e32 v143, v143
	s_waitcnt lgkmcnt(5)
	v_mfma_f32_32x32x16_bf16 v[80:95], v[64:67], v[124:127], 0
	v_exp_f32_e32 v180, v140
	v_exp_f32_e32 v181, v141
	v_exp_f32_e32 v206, v138
	v_exp_f32_e32 v207, v135
	v_exp_f32_e32 v148, v148
	v_exp_f32_e32 v149, v149
	v_exp_f32_e32 v209, v146
	s_waitcnt lgkmcnt(4)
	v_mfma_f32_32x32x16_bf16 v[64:79], v[68:71], v[124:127], 0
	v_cvt_pk_bf16_f32 v135, v192, v193
	v_cvt_pk_bf16_f32 v138, v182, v183
	v_cvt_pk_bf16_f32 v140, v185, v187
	v_cvt_pk_bf16_f32 v141, v188, v189
	s_nop 0
	s_waitcnt lgkmcnt(3)
	v_mfma_f32_32x32x16_bf16 v[80:95], v[176:179], v[120:123], v[80:95]
	ds_read_b128 v[176:179], v169 offset:49152
	ds_read_b128 v[214:217], v169 offset:57344
	ds_read_b128 v[218:221], v170 offset:49152
	ds_read_b128 v[222:225], v170 offset:57344
	ds_read_b128 v[226:229], v171 offset:49152
	ds_read_b128 v[230:233], v171 offset:57344
	ds_read_b128 v[234:237], v172 offset:49152
	ds_read_b128 v[238:241], v172 offset:57344
	s_waitcnt lgkmcnt(10)
	v_mfma_f32_32x32x16_bf16 v[64:79], v[198:201], v[120:123], v[64:79]
	ds_read_b128 v[198:201], v173 offset:49152
	ds_read_b128 v[242:245], v173 offset:57344
	s_waitcnt lgkmcnt(11)
	v_mfma_f32_32x32x16_bf16 v[80:95], v[202:205], v[112:115], v[80:95]
	v_exp_f32_e32 v205, v134
	v_add_f32_e32 v134, v191, v190
	v_add_f32_e32 v134, v192, v134
	v_add_f32_e32 v134, v193, v134
	v_add_f32_e32 v134, v194, v134
	v_add_f32_e32 v134, v196, v134
	s_waitcnt lgkmcnt(10)
	v_mfma_f32_32x32x16_bf16 v[64:79], v[210:213], v[112:115], v[64:79]
	v_add_f32_e32 v134, v195, v134
	v_add_f32_e32 v134, v197, v134
	v_add_f32_e32 v134, v182, v134
	v_add_f32_e32 v134, v183, v134
	v_add_f32_e32 v134, v184, v134
	v_add_f32_e32 v134, v186, v134
	v_add_f32_e32 v134, v185, v134
	s_waitcnt lgkmcnt(9)
	v_mfma_f32_32x32x16_bf16 v[80:95], v[176:179], v[116:119], v[80:95]
	v_add_f32_e32 v134, v187, v134
	v_add_f32_e32 v134, v188, v134
	v_add_f32_e32 v134, v189, v134
	v_add_f32_e32 v134, v142, v134
	v_exp_f32_e32 v202, v139
	v_add_f32_e32 v134, v143, v134
	v_exp_f32_e32 v203, v136
	s_waitcnt lgkmcnt(8)
	v_mfma_f32_32x32x16_bf16 v[64:79], v[214:217], v[116:119], v[64:79]
	v_add_f32_e32 v134, v180, v134
	v_exp_f32_e32 v204, v137
	v_add_f32_e32 v134, v181, v134
	v_add_f32_e32 v134, v206, v134
	v_add_f32_e32 v134, v202, v134
	v_add_f32_e32 v134, v203, v134
	v_add_f32_e32 v134, v204, v134
	s_waitcnt lgkmcnt(7)
	v_mfma_f32_32x32x16_bf16 v[80:95], v[218:221], v[108:111], v[80:95]
	v_add_f32_e32 v134, v205, v134
	v_exp_f32_e32 v210, v147
	v_add_f32_e32 v134, v207, v134
	v_exp_f32_e32 v211, v144
	v_add_f32_e32 v134, v148, v134
	v_exp_f32_e32 v212, v145
	v_add_f32_e32 v134, v149, v134
	s_waitcnt lgkmcnt(6)
	v_mfma_f32_32x32x16_bf16 v[64:79], v[222:225], v[108:111], v[64:79]
	v_add_f32_e32 v134, v209, v134
	v_add_f32_e32 v134, v210, v134
	v_add_f32_e32 v134, v211, v134
	v_add_f32_e32 v176, v212, v134
	v_cvt_pk_bf16_f32 v134, v190, v191
	v_cvt_pk_bf16_f32 v136, v194, v196
	s_waitcnt lgkmcnt(5)
	v_mfma_f32_32x32x16_bf16 v[80:95], v[226:229], v[104:107], v[80:95]
	v_cvt_pk_bf16_f32 v137, v195, v197
	v_cvt_pk_bf16_f32 v139, v184, v186
	v_cvt_pk_bf16_f32 v142, v142, v143
	s_waitcnt lgkmcnt(4)
	v_mfma_f32_32x32x16_bf16 v[64:79], v[230:233], v[104:107], v[64:79]
	v_cvt_pk_bf16_f32 v143, v180, v181
	v_cvt_pk_bf16_f32 v144, v206, v202
	v_cvt_pk_bf16_f32 v145, v203, v204
	v_cvt_pk_bf16_f32 v146, v205, v207
	v_cvt_pk_bf16_f32 v147, v148, v149
	v_cvt_pk_bf16_f32 v148, v209, v210
	v_cvt_pk_bf16_f32 v149, v211, v212
	s_waitcnt lgkmcnt(3)
	v_mfma_f32_32x32x16_bf16 v[80:95], v[234:237], v[100:103], v[80:95]
	s_waitcnt lgkmcnt(2)
	v_mfma_f32_32x32x16_bf16 v[64:79], v[238:241], v[100:103], v[64:79]
	s_waitcnt lgkmcnt(1)
	v_mfma_f32_32x32x16_bf16 v[80:95], v[198:201], v[96:99], v[80:95]
	s_waitcnt lgkmcnt(0)
	v_mfma_f32_32x32x16_bf16 v[64:79], v[242:245], v[96:99], v[64:79]
	global_load_dwordx4 v[180:183], v132, s[28:29]
	global_load_dwordx4 v[184:187], v133, s[28:29]
	global_load_dwordx4 v[188:191], v132, s[30:31]
	global_load_dwordx4 v[192:195], v133, s[30:31]
	s_add_u32 s28, s28, 0x8000
	s_addc_u32 s29, s29, 0
	s_add_u32 s30, s30, 0x8000
	s_addc_u32 s31, s31, 0
	ds_read_b64_tr_b16 v[196:197], v161 offset:0
	ds_read_b64_tr_b16 v[198:199], v161 offset:0x800
	ds_read_b64_tr_b16 v[200:201], v161 offset:0x1000
	ds_read_b64_tr_b16 v[202:203], v161 offset:0x1800
	ds_read_b64_tr_b16 v[204:205], v161 offset:0x2000
	ds_read_b64_tr_b16 v[206:207], v161 offset:0x2800
	ds_read_b64_tr_b16 v[210:211], v161 offset:0x3000
	ds_read_b64_tr_b16 v[212:213], v161 offset:0x3800
	s_waitcnt lgkmcnt(0)
	s_nop 0
	v_mfma_f32_32x32x16_bf16 v[0:15], v[134:137], v[196:199], v[0:15]
	ds_read_b64_tr_b16 v[196:197], v161 offset:0x200
	ds_read_b64_tr_b16 v[198:199], v161 offset:0xa00
	v_mfma_f32_32x32x16_bf16 v[0:15], v[138:141], v[200:203], v[0:15]
	ds_read_b64_tr_b16 v[200:201], v161 offset:0x1200
	ds_read_b64_tr_b16 v[202:203], v161 offset:0x1a00
	v_mfma_f32_32x32x16_bf16 v[0:15], v[142:145], v[204:207], v[0:15]
	ds_read_b64_tr_b16 v[204:205], v161 offset:0x2200
	ds_read_b64_tr_b16 v[206:207], v161 offset:0x2a00
	ds_read_b64_tr_b16 v[214:215], v161 offset:0x3200
	ds_read_b64_tr_b16 v[216:217], v161 offset:0x3a00
	s_waitcnt lgkmcnt(0)
	v_mfma_f32_32x32x16_bf16 v[0:15], v[146:149], v[210:213], v[0:15]
	v_mfma_f32_32x32x16_bf16 v[48:63], v[134:137], v[196:199], v[48:63]
	ds_read_b64_tr_b16 v[196:197], v161 offset:0x400
	ds_read_b64_tr_b16 v[198:199], v161 offset:0xc00
	v_mfma_f32_32x32x16_bf16 v[48:63], v[138:141], v[200:203], v[48:63]
	ds_read_b64_tr_b16 v[200:201], v161 offset:0x1400
	ds_read_b64_tr_b16 v[202:203], v161 offset:0x1c00
	v_mfma_f32_32x32x16_bf16 v[48:63], v[142:145], v[204:207], v[48:63]
	ds_read_b64_tr_b16 v[204:205], v161 offset:0x2400
	ds_read_b64_tr_b16 v[206:207], v161 offset:0x2c00
	ds_read_b64_tr_b16 v[210:211], v161 offset:0x3400
	ds_read_b64_tr_b16 v[212:213], v161 offset:0x3c00
	s_waitcnt lgkmcnt(0)
	v_mfma_f32_32x32x16_bf16 v[48:63], v[146:149], v[214:217], v[48:63]
	v_mfma_f32_32x32x16_bf16 v[32:47], v[134:137], v[196:199], v[32:47]
	ds_read_b64_tr_b16 v[196:197], v161 offset:0x600
	ds_read_b64_tr_b16 v[198:199], v161 offset:0xe00
	v_mfma_f32_32x32x16_bf16 v[32:47], v[138:141], v[200:203], v[32:47]
	ds_read_b64_tr_b16 v[200:201], v161 offset:0x1600
	ds_read_b64_tr_b16 v[202:203], v161 offset:0x1e00
	v_mfma_f32_32x32x16_bf16 v[32:47], v[142:145], v[204:207], v[32:47]
	ds_read_b64_tr_b16 v[204:205], v161 offset:0x2600
	ds_read_b64_tr_b16 v[206:207], v161 offset:0x2e00
	ds_read_b64_tr_b16 v[214:215], v161 offset:0x3600
	ds_read_b64_tr_b16 v[216:217], v161 offset:0x3e00
	s_waitcnt lgkmcnt(0)
	v_mfma_f32_32x32x16_bf16 v[32:47], v[146:149], v[210:213], v[32:47]
	v_mfma_f32_32x32x16_bf16 v[16:31], v[134:137], v[196:199], v[16:31]
	v_max_f32_e32 v177, v80, v81
	v_max3_f32 v177, v177, v82, v83
	v_max3_f32 v177, v177, v84, v85
	v_max3_f32 v134, v177, v86, v87
	v_max3_f32 v134, v134, v88, v89
	v_max3_f32 v134, v134, v90, v91
	v_mfma_f32_32x32x16_bf16 v[16:31], v[138:141], v[200:203], v[16:31]
	v_max3_f32 v134, v134, v92, v93
	v_max3_f32 v134, v134, v94, v95
	v_max3_f32 v134, v134, v64, v65
	v_max3_f32 v134, v134, v66, v67
	v_max3_f32 v134, v134, v68, v69
	v_max3_f32 v134, v134, v70, v71
	v_max3_f32 v134, v134, v72, v73
	v_max3_f32 v134, v134, v74, v75
	v_mfma_f32_32x32x16_bf16 v[16:31], v[142:145], v[204:207], v[16:31]
	v_max3_f32 v134, v134, v76, v77
	v_max3_f32 v134, v134, v78, v79
	v_mov_b32_e32 v135, v134
	s_nop 1
	v_permlane32_swap_b32_e32 v134, v135
	v_max_f32_e32 v134, v134, v135
	v_sub_f32_e32 v135, v134, v175
	v_max_f32_e32 v134, v175, v134
	v_mfma_f32_32x32x16_bf16 v[16:31], v[146:149], v[214:217], v[16:31]
	v_sub_f32_e32 v136, v175, v134
	v_mul_f32_e32 v136, 0x3e0293ee, v136
	v_exp_f32_e32 v136, v136
	v_cmp_ge_f32_e32 vcc, s15, v135
	s_cmp_eq_u64 vcc, exec
	s_cselect_b64 s[8:9], -1, 0
	s_barrier
	s_waitcnt vmcnt(0)
	v_cndmask_b32_e64 v179, v136, 1.0, s[8:9]
	v_cmp_gt_f32_e32 vcc, 1.0, v179
	s_waitcnt vmcnt(3)
	ds_write_b128 v164, v[180:183]
	s_waitcnt vmcnt(2)
	ds_write_b128 v165, v[184:187]
	s_waitcnt vmcnt(1)
	ds_write_b128 v162, v[188:191] offset:32768
	s_waitcnt vmcnt(0)
	ds_write_b128 v163, v[192:195] offset:32768
	s_cbranch_vccz .LBB0_437
	s_and_saveexec_b64 s[2:3], s[6:7]
	ds_write_b32 v158, v179 offset:128
	s_or_b64 exec, exec, s[2:3]
	s_waitcnt lgkmcnt(0)
	v_add_u32_e32 v135, v131, v128
	ds_read_b128 v[136:139], v135 offset:224
	ds_read_b128 v[140:143], v135 offset:192
	ds_read_b128 v[144:147], v135 offset:160
	ds_read_b128 v[180:183], v135 offset:128
	s_waitcnt lgkmcnt(3)
	v_pk_mul_f32 v[12:13], v[12:13], v[136:137]
	s_waitcnt lgkmcnt(2)
	v_pk_mul_f32 v[8:9], v[8:9], v[140:141]
	s_waitcnt lgkmcnt(1)
	v_pk_mul_f32 v[4:5], v[4:5], v[144:145]
	v_pk_mul_f32 v[14:15], v[14:15], v[138:139]
	v_pk_mul_f32 v[10:11], v[10:11], v[142:143]
	v_pk_mul_f32 v[6:7], v[6:7], v[146:147]
	s_waitcnt lgkmcnt(0)
	v_pk_mul_f32 v[2:3], v[2:3], v[182:183]
	v_pk_mul_f32 v[0:1], v[0:1], v[180:181]
	v_pk_mul_f32 v[60:61], v[60:61], v[136:137]
	v_pk_mul_f32 v[56:57], v[56:57], v[140:141]
	v_pk_mul_f32 v[52:53], v[52:53], v[144:145]
	v_pk_mul_f32 v[62:63], v[62:63], v[138:139]
	v_pk_mul_f32 v[58:59], v[58:59], v[142:143]
	v_pk_mul_f32 v[54:55], v[54:55], v[146:147]
	v_pk_mul_f32 v[50:51], v[50:51], v[182:183]
	v_pk_mul_f32 v[48:49], v[48:49], v[180:181]
	v_pk_mul_f32 v[44:45], v[44:45], v[136:137]
	v_pk_mul_f32 v[40:41], v[40:41], v[140:141]
	v_pk_mul_f32 v[36:37], v[36:37], v[144:145]
	v_pk_mul_f32 v[46:47], v[46:47], v[138:139]
	v_pk_mul_f32 v[42:43], v[42:43], v[142:143]
	v_pk_mul_f32 v[38:39], v[38:39], v[146:147]
	v_pk_mul_f32 v[34:35], v[34:35], v[182:183]
	v_pk_mul_f32 v[32:33], v[32:33], v[180:181]
	v_pk_mul_f32 v[28:29], v[28:29], v[136:137]
	v_pk_mul_f32 v[24:25], v[24:25], v[140:141]
	v_pk_mul_f32 v[20:21], v[20:21], v[144:145]
	v_pk_mul_f32 v[30:31], v[30:31], v[138:139]
	v_pk_mul_f32 v[26:27], v[26:27], v[142:143]
	v_pk_mul_f32 v[22:23], v[22:23], v[146:147]
	v_pk_mul_f32 v[18:19], v[18:19], v[182:183]
	v_pk_mul_f32 v[16:17], v[16:17], v[180:181]
.LBB0_437:
	v_cndmask_b32_e64 v134, v134, v175, s[8:9]
	v_mul_f32_e32 v196, 0xbe0293ee, v134
	v_pk_fma_f32 v[88:89], v[88:89], s[14:15], v[196:197] op_sel_hi:[1,0,0]
	v_pk_fma_f32 v[80:81], v[80:81], s[14:15], v[196:197] op_sel_hi:[1,0,0]
	v_pk_fma_f32 v[82:83], v[82:83], s[14:15], v[196:197] op_sel_hi:[1,0,0]
	v_pk_fma_f32 v[84:85], v[84:85], s[14:15], v[196:197] op_sel_hi:[1,0,0]
	v_pk_fma_f32 v[86:87], v[86:87], s[14:15], v[196:197] op_sel_hi:[1,0,0]
	v_pk_fma_f32 v[90:91], v[90:91], s[14:15], v[196:197] op_sel_hi:[1,0,0]
	v_pk_fma_f32 v[92:93], v[92:93], s[14:15], v[196:197] op_sel_hi:[1,0,0]
	v_pk_fma_f32 v[94:95], v[94:95], s[14:15], v[196:197] op_sel_hi:[1,0,0]
	v_exp_f32_e32 v135, v88
	v_pk_fma_f32 v[188:189], v[64:65], s[14:15], v[196:197] op_sel_hi:[1,0,0]
	v_pk_fma_f32 v[190:191], v[66:67], s[14:15], v[196:197] op_sel_hi:[1,0,0]
	v_fmamk_f32 v192, v68, 0x3e0293ee, v196
	v_fmamk_f32 v181, v69, 0x3e0293ee, v196
	v_pk_fma_f32 v[182:183], v[70:71], s[14:15], v[196:197] op_sel_hi:[1,0,0]
	v_pk_fma_f32 v[184:185], v[72:73], s[14:15], v[196:197] op_sel_hi:[1,0,0]
	v_pk_fma_f32 v[186:187], v[74:75], s[14:15], v[196:197] op_sel_hi:[1,0,0]
	v_fmamk_f32 v180, v76, 0x3e0293ee, v196
	v_fmamk_f32 v193, v77, 0x3e0293ee, v196
	v_fmamk_f32 v194, v78, 0x3e0293ee, v196
	v_fmamk_f32 v177, v79, 0x3e0293ee, v196
	v_exp_f32_e32 v143, v80
	v_exp_f32_e32 v144, v81
	v_exp_f32_e32 v145, v82
	v_exp_f32_e32 v146, v83
	v_exp_f32_e32 v147, v84
	v_exp_f32_e32 v149, v85
	v_exp_f32_e32 v148, v86
	v_exp_f32_e32 v175, v87
	v_exp_f32_e32 v136, v89
	v_exp_f32_e32 v137, v90
	v_exp_f32_e32 v139, v91
	v_exp_f32_e32 v138, v92
	v_exp_f32_e32 v140, v93
	v_exp_f32_e32 v141, v94
	v_exp_f32_e32 v142, v95
	s_waitcnt lgkmcnt(0)
	s_barrier
	ds_read_b128 v[64:67], v166 offset:32768
	ds_read_b128 v[68:71], v166 offset:40960
	ds_read_b128 v[196:199], v167 offset:32768
	ds_read_b128 v[200:203], v167 offset:40960
	ds_read_b128 v[204:207], v168 offset:32768
	ds_read_b128 v[210:213], v168 offset:40960
	v_exp_f32_e32 v188, v188
	v_exp_f32_e32 v189, v189
	s_waitcnt lgkmcnt(5)
	v_mfma_f32_32x32x16_bf16 v[80:95], v[64:67], v[124:127], 0
	v_exp_f32_e32 v190, v190
	v_exp_f32_e32 v191, v191
	v_exp_f32_e32 v192, v192
	v_exp_f32_e32 v195, v181
	v_exp_f32_e32 v182, v182
	v_exp_f32_e32 v183, v183
	v_exp_f32_e32 v184, v184
	s_waitcnt lgkmcnt(4)
	v_mfma_f32_32x32x16_bf16 v[64:79], v[68:71], v[124:127], 0
	v_exp_f32_e32 v185, v185
	v_exp_f32_e32 v186, v186
	v_exp_f32_e32 v187, v187
	v_exp_f32_e32 v193, v193
	v_exp_f32_e32 v194, v194
	v_exp_f32_e32 v177, v177
	s_waitcnt lgkmcnt(3)
	v_mfma_f32_32x32x16_bf16 v[80:95], v[196:199], v[120:123], v[80:95]
	ds_read_b128 v[196:199], v169 offset:32768
	ds_read_b128 v[214:217], v169 offset:40960
	ds_read_b128 v[218:221], v170 offset:32768
	ds_read_b128 v[222:225], v170 offset:40960
	ds_read_b128 v[226:229], v171 offset:32768
	ds_read_b128 v[230:233], v171 offset:40960
	ds_read_b128 v[234:237], v172 offset:32768
	ds_read_b128 v[238:241], v172 offset:40960
	s_waitcnt lgkmcnt(10)
	v_mfma_f32_32x32x16_bf16 v[64:79], v[200:203], v[120:123], v[64:79]
	ds_read_b128 v[200:203], v173 offset:32768
	ds_read_b128 v[242:245], v173 offset:40960
	s_waitcnt lgkmcnt(11)
	v_mfma_f32_32x32x16_bf16 v[80:95], v[204:207], v[112:115], v[80:95]
	v_exp_f32_e32 v204, v180
	v_add_f32_e32 v180, v144, v143
	v_add_f32_e32 v180, v145, v180
	v_add_f32_e32 v180, v146, v180
	v_add_f32_e32 v180, v147, v180
	v_add_f32_e32 v180, v149, v180
	s_waitcnt lgkmcnt(10)
	v_mfma_f32_32x32x16_bf16 v[64:79], v[210:213], v[112:115], v[64:79]
	v_add_f32_e32 v180, v148, v180
	v_add_f32_e32 v180, v175, v180
	v_add_f32_e32 v180, v135, v180
	v_add_f32_e32 v180, v136, v180
	v_add_f32_e32 v180, v137, v180
	v_add_f32_e32 v180, v139, v180
	v_add_f32_e32 v180, v138, v180
	s_waitcnt lgkmcnt(9)
	v_mfma_f32_32x32x16_bf16 v[80:95], v[196:199], v[116:119], v[80:95]
	v_add_f32_e32 v180, v140, v180
	v_add_f32_e32 v180, v141, v180
	v_add_f32_e32 v180, v142, v180
	v_add_f32_e32 v180, v188, v180
	v_add_f32_e32 v180, v189, v180
	v_add_f32_e32 v180, v190, v180
	v_add_f32_e32 v180, v191, v180
	s_waitcnt lgkmcnt(8)
	v_mfma_f32_32x32x16_bf16 v[64:79], v[214:217], v[116:119], v[64:79]
	v_add_f32_e32 v180, v192, v180
	v_add_f32_e32 v180, v195, v180
	v_add_f32_e32 v180, v182, v180
	v_add_f32_e32 v180, v183, v180
	v_add_f32_e32 v180, v184, v180
	v_add_f32_e32 v180, v185, v180
	v_add_f32_e32 v180, v186, v180
	s_waitcnt lgkmcnt(7)
	v_mfma_f32_32x32x16_bf16 v[80:95], v[218:221], v[108:111], v[80:95]
	v_add_f32_e32 v180, v187, v180
	v_add_f32_e32 v180, v204, v180
	v_add_f32_e32 v180, v193, v180
	v_add_f32_e32 v180, v194, v180
	v_add_f32_e32 v180, v177, v180
	s_waitcnt lgkmcnt(6)
	v_mfma_f32_32x32x16_bf16 v[64:79], v[222:225], v[108:111], v[64:79]
	v_cvt_pk_bf16_f32 v144, v143, v144
	v_cvt_pk_bf16_f32 v145, v145, v146
	v_cvt_pk_bf16_f32 v146, v147, v149
	v_cvt_pk_bf16_f32 v147, v148, v175
	v_cvt_pk_bf16_f32 v136, v135, v136
	v_cvt_pk_bf16_f32 v137, v137, v139
	v_cvt_pk_bf16_f32 v138, v138, v140
	s_waitcnt lgkmcnt(5)
	v_mfma_f32_32x32x16_bf16 v[80:95], v[226:229], v[104:107], v[80:95]
	v_cvt_pk_bf16_f32 v139, v141, v142
	v_cvt_pk_bf16_f32 v140, v188, v189
	v_cvt_pk_bf16_f32 v141, v190, v191
	v_cvt_pk_bf16_f32 v142, v192, v195
	v_cvt_pk_bf16_f32 v143, v182, v183
	v_cvt_pk_bf16_f32 v182, v184, v185
	v_cvt_pk_bf16_f32 v183, v186, v187
	s_waitcnt lgkmcnt(4)
	v_mfma_f32_32x32x16_bf16 v[64:79], v[230:233], v[104:107], v[64:79]
	v_cvt_pk_bf16_f32 v184, v204, v193
	v_cvt_pk_bf16_f32 v185, v194, v177
	s_waitcnt lgkmcnt(3)
	v_mfma_f32_32x32x16_bf16 v[80:95], v[234:237], v[100:103], v[80:95]
	s_waitcnt lgkmcnt(2)
	v_mfma_f32_32x32x16_bf16 v[64:79], v[238:241], v[100:103], v[64:79]
	s_waitcnt lgkmcnt(1)
	v_mfma_f32_32x32x16_bf16 v[80:95], v[200:203], v[96:99], v[80:95]
	s_waitcnt lgkmcnt(0)
	v_mfma_f32_32x32x16_bf16 v[64:79], v[242:245], v[96:99], v[64:79]
	global_load_dwordx4 v[186:189], v132, s[28:29]
	global_load_dwordx4 v[190:193], v132, s[30:31]
	global_load_dwordx4 v[194:197], v133, s[28:29]
	global_load_dwordx4 v[198:201], v133, s[30:31]
	s_add_u32 s28, s28, 0x8000
	s_addc_u32 s29, s29, 0
	s_add_u32 s30, s30, 0x8000
	s_addc_u32 s31, s31, 0
	ds_read_b64_tr_b16 v[202:203], v160 offset:0
	ds_read_b64_tr_b16 v[204:205], v160 offset:0x800
	ds_read_b64_tr_b16 v[210:211], v160 offset:0x1000
	ds_read_b64_tr_b16 v[212:213], v160 offset:0x1800
	ds_read_b64_tr_b16 v[214:215], v160 offset:0x2000
	ds_read_b64_tr_b16 v[216:217], v160 offset:0x2800
	ds_read_b64_tr_b16 v[218:219], v160 offset:0x3000
	ds_read_b64_tr_b16 v[220:221], v160 offset:0x3800
	s_waitcnt lgkmcnt(0)
	s_nop 0
	v_mfma_f32_32x32x16_bf16 v[0:15], v[144:147], v[202:205], v[0:15]
	ds_read_b64_tr_b16 v[202:203], v160 offset:0x200
	ds_read_b64_tr_b16 v[204:205], v160 offset:0xa00
	v_mfma_f32_32x32x16_bf16 v[0:15], v[136:139], v[210:213], v[0:15]
	ds_read_b64_tr_b16 v[210:211], v160 offset:0x1200
	ds_read_b64_tr_b16 v[212:213], v160 offset:0x1a00
	v_mfma_f32_32x32x16_bf16 v[0:15], v[140:143], v[214:217], v[0:15]
	ds_read_b64_tr_b16 v[214:215], v160 offset:0x2200
	ds_read_b64_tr_b16 v[216:217], v160 offset:0x2a00
	ds_read_b64_tr_b16 v[222:223], v160 offset:0x3200
	ds_read_b64_tr_b16 v[224:225], v160 offset:0x3a00
	s_waitcnt lgkmcnt(0)
	v_mfma_f32_32x32x16_bf16 v[0:15], v[182:185], v[218:221], v[0:15]
	v_mfma_f32_32x32x16_bf16 v[48:63], v[144:147], v[202:205], v[48:63]
	ds_read_b64_tr_b16 v[202:203], v160 offset:0x400
	ds_read_b64_tr_b16 v[204:205], v160 offset:0xc00
	v_mfma_f32_32x32x16_bf16 v[48:63], v[136:139], v[210:213], v[48:63]
	ds_read_b64_tr_b16 v[210:211], v160 offset:0x1400
	ds_read_b64_tr_b16 v[212:213], v160 offset:0x1c00
	v_mfma_f32_32x32x16_bf16 v[48:63], v[140:143], v[214:217], v[48:63]
	ds_read_b64_tr_b16 v[214:215], v160 offset:0x2400
	ds_read_b64_tr_b16 v[216:217], v160 offset:0x2c00
	ds_read_b64_tr_b16 v[218:219], v160 offset:0x3400
	ds_read_b64_tr_b16 v[220:221], v160 offset:0x3c00
	s_waitcnt lgkmcnt(0)
	v_mfma_f32_32x32x16_bf16 v[48:63], v[182:185], v[222:225], v[48:63]
	v_mfma_f32_32x32x16_bf16 v[32:47], v[144:147], v[202:205], v[32:47]
	ds_read_b64_tr_b16 v[202:203], v160 offset:0x600
	ds_read_b64_tr_b16 v[204:205], v160 offset:0xe00
	v_mfma_f32_32x32x16_bf16 v[32:47], v[136:139], v[210:213], v[32:47]
	ds_read_b64_tr_b16 v[210:211], v160 offset:0x1600
	ds_read_b64_tr_b16 v[212:213], v160 offset:0x1e00
	v_mfma_f32_32x32x16_bf16 v[32:47], v[140:143], v[214:217], v[32:47]
	ds_read_b64_tr_b16 v[214:215], v160 offset:0x2600
	ds_read_b64_tr_b16 v[216:217], v160 offset:0x2e00
	ds_read_b64_tr_b16 v[222:223], v160 offset:0x3600
	ds_read_b64_tr_b16 v[224:225], v160 offset:0x3e00
	s_waitcnt lgkmcnt(0)
	v_mfma_f32_32x32x16_bf16 v[32:47], v[182:185], v[218:221], v[32:47]
	v_mfma_f32_32x32x16_bf16 v[16:31], v[144:147], v[202:205], v[16:31]
	v_max_f32_e32 v135, v80, v81
	v_max3_f32 v135, v135, v82, v83
	v_max3_f32 v135, v135, v84, v85
	v_max3_f32 v135, v135, v86, v87
	v_max3_f32 v135, v135, v88, v89
	v_max3_f32 v135, v135, v90, v91
	v_mfma_f32_32x32x16_bf16 v[16:31], v[136:139], v[210:213], v[16:31]
	v_max3_f32 v135, v135, v92, v93
	v_max3_f32 v135, v135, v94, v95
	v_max3_f32 v135, v135, v64, v65
	v_max3_f32 v135, v135, v66, v67
	v_max3_f32 v135, v135, v68, v69
	v_max3_f32 v135, v135, v70, v71
	v_max3_f32 v135, v135, v72, v73
	v_max3_f32 v135, v135, v74, v75
	v_mfma_f32_32x32x16_bf16 v[16:31], v[140:143], v[214:217], v[16:31]
	v_max3_f32 v135, v135, v76, v77
	v_max3_f32 v135, v135, v78, v79
	v_mov_b32_e32 v136, v135
	s_nop 1
	v_permlane32_swap_b32_e32 v135, v136
	v_max_f32_e32 v135, v135, v136
	v_sub_f32_e32 v136, v135, v134
	v_max_f32_e32 v135, v134, v135
	v_mfma_f32_32x32x16_bf16 v[16:31], v[182:185], v[222:225], v[16:31]
	v_sub_f32_e32 v137, v134, v135
	v_mul_f32_e32 v137, 0x3e0293ee, v137
	v_exp_f32_e32 v137, v137
	v_cmp_ge_f32_e32 vcc, s15, v136
	s_cmp_eq_u64 vcc, exec
	s_cselect_b64 s[8:9], -1, 0
	s_barrier
	s_waitcnt vmcnt(0)
	v_cndmask_b32_e64 v177, v137, 1.0, s[8:9]
	v_cmp_gt_f32_e32 vcc, 1.0, v177
	s_waitcnt vmcnt(3)
	ds_write_b128 v164, v[186:189] offset:16384
	s_waitcnt vmcnt(1)
	ds_write_b128 v165, v[194:197] offset:16384
	ds_write_b128 v162, v[190:193] offset:49152
	s_waitcnt vmcnt(0)
	ds_write_b128 v163, v[198:201] offset:49152
	s_cbranch_vccz .LBB0_441
	s_and_saveexec_b64 s[2:3], s[6:7]
	ds_write_b32 v158, v177 offset:128
	s_or_b64 exec, exec, s[2:3]
	s_waitcnt lgkmcnt(0)
	v_add_u32_e32 v148, v131, v128
	ds_read_b128 v[136:139], v148 offset:224
	ds_read_b128 v[140:143], v148 offset:192
	ds_read_b128 v[144:147], v148 offset:160
	ds_read_b128 v[182:185], v148 offset:128
	s_waitcnt lgkmcnt(3)
	v_pk_mul_f32 v[12:13], v[12:13], v[136:137]
	s_waitcnt lgkmcnt(2)
	v_pk_mul_f32 v[8:9], v[8:9], v[140:141]
	s_waitcnt lgkmcnt(1)
	v_pk_mul_f32 v[4:5], v[4:5], v[144:145]
	v_pk_mul_f32 v[14:15], v[14:15], v[138:139]
	v_pk_mul_f32 v[10:11], v[10:11], v[142:143]
	v_pk_mul_f32 v[6:7], v[6:7], v[146:147]
	s_waitcnt lgkmcnt(0)
	v_pk_mul_f32 v[2:3], v[2:3], v[184:185]
	v_pk_mul_f32 v[0:1], v[0:1], v[182:183]
	v_pk_mul_f32 v[60:61], v[60:61], v[136:137]
	v_pk_mul_f32 v[56:57], v[56:57], v[140:141]
	v_pk_mul_f32 v[52:53], v[52:53], v[144:145]
	v_pk_mul_f32 v[62:63], v[62:63], v[138:139]
	v_pk_mul_f32 v[58:59], v[58:59], v[142:143]
	v_pk_mul_f32 v[54:55], v[54:55], v[146:147]
	v_pk_mul_f32 v[50:51], v[50:51], v[184:185]
	v_pk_mul_f32 v[48:49], v[48:49], v[182:183]
	v_pk_mul_f32 v[44:45], v[44:45], v[136:137]
	v_pk_mul_f32 v[40:41], v[40:41], v[140:141]
	v_pk_mul_f32 v[36:37], v[36:37], v[144:145]
	v_pk_mul_f32 v[46:47], v[46:47], v[138:139]
	v_pk_mul_f32 v[42:43], v[42:43], v[142:143]
	v_pk_mul_f32 v[38:39], v[38:39], v[146:147]
	v_pk_mul_f32 v[34:35], v[34:35], v[184:185]
	v_pk_mul_f32 v[32:33], v[32:33], v[182:183]
	v_pk_mul_f32 v[28:29], v[28:29], v[136:137]
	v_pk_mul_f32 v[24:25], v[24:25], v[140:141]
	v_pk_mul_f32 v[20:21], v[20:21], v[144:145]
	v_pk_mul_f32 v[30:31], v[30:31], v[138:139]
	v_pk_mul_f32 v[26:27], v[26:27], v[142:143]
	v_pk_mul_f32 v[22:23], v[22:23], v[146:147]
	v_pk_mul_f32 v[18:19], v[18:19], v[184:185]
	v_pk_mul_f32 v[16:17], v[16:17], v[182:183]

.LBB0_443:
	v_mov_b32_e32 v178, v159
	s_nop 1
	v_permlane32_swap_b32_e32 v159, v178
	v_add_f32_e32 v159, v159, v178
	ds_read_b128 v[64:67], v166 offset:49152
	ds_read_b128 v[68:71], v166 offset:57344
	v_exp_f32_e32 v132, v142
	v_exp_f32_e32 v133, v143
	v_exp_f32_e32 v140, v140
	s_waitcnt lgkmcnt(1)
	v_mfma_f32_32x32x16_bf16 v[80:95], v[64:67], v[124:127], 0
	v_exp_f32_e32 v141, v141
	v_exp_f32_e32 v138, v138
	v_exp_f32_e32 v139, v139
	v_exp_f32_e32 v136, v136
	v_exp_f32_e32 v137, v137
	v_exp_f32_e32 v134, v134
	v_exp_f32_e32 v135, v135
	s_waitcnt lgkmcnt(0)
	v_mfma_f32_32x32x16_bf16 v[64:79], v[68:71], v[124:127], 0
	ds_read_b128 v[124:127], v167 offset:49152
	ds_read_b128 v[162:165], v167 offset:57344
	ds_read_b128 v[178:181], v168 offset:49152
	ds_read_b128 v[198:201], v168 offset:57344
	v_exp_f32_e32 v142, v148
	v_exp_f32_e32 v143, v149
	v_exp_f32_e32 v146, v146
	v_exp_f32_e32 v147, v147
	v_exp_f32_e32 v144, v144
	v_exp_f32_e32 v145, v145
	s_waitcnt lgkmcnt(3)
	v_mfma_f32_32x32x16_bf16 v[80:95], v[124:127], v[120:123], v[80:95]
	ds_read_b128 v[124:127], v169 offset:49152
	ds_read_b128 v[166:169], v169 offset:57344
	ds_read_b128 v[202:205], v170 offset:49152
	ds_read_b128 v[210:213], v170 offset:57344
	ds_read_b128 v[214:217], v171 offset:49152
	ds_read_b128 v[218:221], v171 offset:57344
	ds_read_b128 v[222:225], v172 offset:49152
	ds_read_b128 v[226:229], v172 offset:57344
	s_waitcnt lgkmcnt(10)
	v_mfma_f32_32x32x16_bf16 v[64:79], v[162:165], v[120:123], v[64:79]
	ds_read_b128 v[120:123], v173 offset:49152
	ds_read_b128 v[162:165], v173 offset:57344
	s_waitcnt lgkmcnt(11)
	v_mfma_f32_32x32x16_bf16 v[80:95], v[178:181], v[112:115], v[80:95]
	s_waitcnt lgkmcnt(10)
	v_mfma_f32_32x32x16_bf16 v[64:79], v[198:201], v[112:115], v[64:79]
	v_add_f32_e32 v112, 0, v190
	v_add_f32_e32 v112, v191, v112
	v_add_f32_e32 v112, v192, v112
	v_add_f32_e32 v112, v193, v112
	v_add_f32_e32 v112, v194, v112
	v_add_f32_e32 v112, v196, v112
	v_add_f32_e32 v112, v195, v112
	s_waitcnt lgkmcnt(9)
	v_mfma_f32_32x32x16_bf16 v[80:95], v[124:127], v[116:119], v[80:95]
	v_add_f32_e32 v112, v197, v112
	v_add_f32_e32 v112, v182, v112
	v_add_f32_e32 v112, v183, v112
	v_add_f32_e32 v112, v184, v112
	v_add_f32_e32 v112, v186, v112
	v_add_f32_e32 v112, v185, v112
	v_add_f32_e32 v112, v187, v112
	s_waitcnt lgkmcnt(8)
	v_mfma_f32_32x32x16_bf16 v[64:79], v[166:169], v[116:119], v[64:79]
	v_add_f32_e32 v112, v188, v112
	v_add_f32_e32 v112, v189, v112
	v_add_f32_e32 v112, v132, v112
	v_add_f32_e32 v112, v133, v112
	v_add_f32_e32 v112, v140, v112
	v_add_f32_e32 v112, v141, v112
	v_add_f32_e32 v112, v138, v112
	s_waitcnt lgkmcnt(7)
	v_mfma_f32_32x32x16_bf16 v[80:95], v[202:205], v[108:111], v[80:95]
	v_add_f32_e32 v112, v139, v112
	v_add_f32_e32 v112, v136, v112
	v_add_f32_e32 v112, v137, v112
	v_cvt_pk_bf16_f32 v113, v195, v197
	v_cvt_pk_bf16_f32 v114, v132, v133
	v_cvt_pk_bf16_f32 v115, v140, v141
	v_cvt_pk_bf16_f32 v116, v138, v139
	s_waitcnt lgkmcnt(6)
	v_mfma_f32_32x32x16_bf16 v[64:79], v[210:213], v[108:111], v[64:79]
	v_add_f32_e32 v108, v134, v112
	v_add_f32_e32 v108, v135, v108
	v_add_f32_e32 v108, v142, v108
	v_add_f32_e32 v108, v143, v108
	v_add_f32_e32 v108, v146, v108
	v_add_f32_e32 v108, v147, v108
	v_add_f32_e32 v108, v144, v108
	s_waitcnt lgkmcnt(5)
	v_mfma_f32_32x32x16_bf16 v[80:95], v[214:217], v[104:107], v[80:95]
	v_add_f32_e32 v108, v145, v108
	v_mov_b32_e32 v109, v108
	s_nop 1
	v_permlane32_swap_b32_e32 v108, v109
	v_cvt_pk_bf16_f32 v110, v190, v191
	v_cvt_pk_bf16_f32 v111, v192, v193
	v_cvt_pk_bf16_f32 v112, v194, v196
	s_waitcnt lgkmcnt(4)
	v_mfma_f32_32x32x16_bf16 v[64:79], v[218:221], v[104:107], v[64:79]
	v_cvt_pk_bf16_f32 v104, v182, v183
	v_cvt_pk_bf16_f32 v105, v184, v186
	v_cvt_pk_bf16_f32 v106, v185, v187
	v_cvt_pk_bf16_f32 v107, v188, v189
	v_cvt_pk_bf16_f32 v117, v136, v137
	s_waitcnt lgkmcnt(3)
	v_mfma_f32_32x32x16_bf16 v[80:95], v[222:225], v[100:103], v[80:95]
	s_waitcnt lgkmcnt(2)
	v_mfma_f32_32x32x16_bf16 v[64:79], v[226:229], v[100:103], v[64:79]
	v_cvt_pk_bf16_f32 v100, v134, v135
	v_cvt_pk_bf16_f32 v101, v142, v143
	v_cvt_pk_bf16_f32 v102, v146, v147
	v_cvt_pk_bf16_f32 v103, v144, v145
	s_waitcnt lgkmcnt(1)
	v_mfma_f32_32x32x16_bf16 v[80:95], v[120:123], v[96:99], v[80:95]
	s_waitcnt lgkmcnt(0)
	v_mfma_f32_32x32x16_bf16 v[64:79], v[162:165], v[96:99], v[64:79]
	ds_read_b64_tr_b16 v[96:97], v161 offset:0
	ds_read_b64_tr_b16 v[98:99], v161 offset:0x800
	ds_read_b64_tr_b16 v[118:119], v161 offset:0x1000
	ds_read_b64_tr_b16 v[120:121], v161 offset:0x1800
	ds_read_b64_tr_b16 v[122:123], v161 offset:0x2000
	ds_read_b64_tr_b16 v[124:125], v161 offset:0x2800
	ds_read_b64_tr_b16 v[132:133], v161 offset:0x3000
	ds_read_b64_tr_b16 v[134:135], v161 offset:0x3800
	s_waitcnt lgkmcnt(0)
	s_nop 0
	v_mfma_f32_32x32x16_bf16 v[0:15], v[110:113], v[96:99], v[0:15]
	ds_read_b64_tr_b16 v[96:97], v161 offset:0x200
	ds_read_b64_tr_b16 v[98:99], v161 offset:0xa00
	v_mfma_f32_32x32x16_bf16 v[0:15], v[104:107], v[118:121], v[0:15]
	ds_read_b64_tr_b16 v[118:119], v161 offset:0x1200
	ds_read_b64_tr_b16 v[120:121], v161 offset:0x1a00
	v_mfma_f32_32x32x16_bf16 v[0:15], v[114:117], v[122:125], v[0:15]
	ds_read_b64_tr_b16 v[122:123], v161 offset:0x2200
	ds_read_b64_tr_b16 v[124:125], v161 offset:0x2a00
	ds_read_b64_tr_b16 v[136:137], v161 offset:0x3200
	ds_read_b64_tr_b16 v[138:139], v161 offset:0x3a00
	s_waitcnt lgkmcnt(0)
	v_mfma_f32_32x32x16_bf16 v[0:15], v[100:103], v[132:135], v[0:15]
	v_mfma_f32_32x32x16_bf16 v[48:63], v[110:113], v[96:99], v[48:63]
	ds_read_b64_tr_b16 v[96:97], v161 offset:0x400
	ds_read_b64_tr_b16 v[98:99], v161 offset:0xc00
	v_mfma_f32_32x32x16_bf16 v[48:63], v[104:107], v[118:121], v[48:63]
	ds_read_b64_tr_b16 v[118:119], v161 offset:0x1400
	ds_read_b64_tr_b16 v[120:121], v161 offset:0x1c00
	v_mfma_f32_32x32x16_bf16 v[48:63], v[114:117], v[122:125], v[48:63]
	ds_read_b64_tr_b16 v[122:123], v161 offset:0x2400
	ds_read_b64_tr_b16 v[124:125], v161 offset:0x2c00
	ds_read_b64_tr_b16 v[132:133], v161 offset:0x3400
	ds_read_b64_tr_b16 v[134:135], v161 offset:0x3c00
	s_waitcnt lgkmcnt(0)
	v_mfma_f32_32x32x16_bf16 v[48:63], v[100:103], v[136:139], v[48:63]
	v_mfma_f32_32x32x16_bf16 v[32:47], v[110:113], v[96:99], v[32:47]
	ds_read_b64_tr_b16 v[96:97], v161 offset:0x600
	ds_read_b64_tr_b16 v[98:99], v161 offset:0xe00
	v_mfma_f32_32x32x16_bf16 v[32:47], v[104:107], v[118:121], v[32:47]
	ds_read_b64_tr_b16 v[118:119], v161 offset:0x1600
	ds_read_b64_tr_b16 v[120:121], v161 offset:0x1e00
	v_mfma_f32_32x32x16_bf16 v[32:47], v[114:117], v[122:125], v[32:47]
	ds_read_b64_tr_b16 v[122:123], v161 offset:0x2600
	ds_read_b64_tr_b16 v[124:125], v161 offset:0x2e00
	ds_read_b64_tr_b16 v[136:137], v161 offset:0x3600
	ds_read_b64_tr_b16 v[138:139], v161 offset:0x3e00
	s_waitcnt lgkmcnt(0)
	v_mfma_f32_32x32x16_bf16 v[32:47], v[100:103], v[132:135], v[32:47]
	v_mfma_f32_32x32x16_bf16 v[16:31], v[110:113], v[96:99], v[16:31]
	v_max_f32_e32 v126, v81, v81
	v_max_f32_e32 v127, v80, v80
	v_max_f32_e32 v126, v127, v126
	v_max3_f32 v126, v126, v82, v83
	v_max3_f32 v126, v126, v84, v85
	v_max3_f32 v96, v126, v86, v87
	v_max3_f32 v96, v96, v88, v89
	v_max3_f32 v96, v96, v90, v91
	v_mfma_f32_32x32x16_bf16 v[16:31], v[104:107], v[118:121], v[16:31]
	v_max3_f32 v96, v96, v92, v93
	v_max3_f32 v96, v96, v94, v95
	v_max3_f32 v96, v96, v64, v65
	v_max3_f32 v96, v96, v66, v67
	v_max3_f32 v96, v96, v68, v69
	v_max3_f32 v96, v96, v70, v71
	v_max3_f32 v96, v96, v72, v73
	v_max3_f32 v96, v96, v74, v75
	v_mfma_f32_32x32x16_bf16 v[16:31], v[114:117], v[122:125], v[16:31]
	v_max3_f32 v96, v96, v76, v77
	v_max3_f32 v96, v96, v78, v79
	v_mov_b32_e32 v97, v96
	s_nop 1
	v_permlane32_swap_b32_e32 v96, v97
	v_max_f32_e32 v97, v97, v97
	v_max_f32_e32 v96, v96, v96
	v_max_f32_e32 v96, v96, v97
	v_max_f32_e32 v97, v175, v175
	v_max_f32_e32 v97, v97, v96
	v_sub_f32_e32 v98, v96, v175
	v_mfma_f32_32x32x16_bf16 v[16:31], v[100:103], v[136:139], v[16:31]
	v_sub_f32_e32 v96, v175, v97
	v_mul_f32_e32 v96, 0x3e0293ee, v96
	v_exp_f32_e32 v96, v96
	v_cmp_ge_f32_e32 vcc, s15, v98
	s_cmp_eq_u64 vcc, exec
	s_cselect_b64 s[8:9], -1, 0
	v_cndmask_b32_e64 v96, v96, 1.0, s[8:9]
	v_cmp_gt_f32_e32 vcc, 1.0, v96
	s_barrier
	s_cbranch_vccz .LBB0_447
	s_and_saveexec_b64 s[2:3], s[6:7]
	ds_write_b32 v158, v96 offset:128
	s_or_b64 exec, exec, s[2:3]
	s_waitcnt lgkmcnt(0)
	v_add_u32_e32 v106, v131, v128
	ds_read_b128 v[98:101], v106 offset:224
	ds_read_b128 v[102:105], v106 offset:192
	ds_read_b128 v[110:113], v106 offset:160
	ds_read_b128 v[114:117], v106 offset:128
	s_waitcnt lgkmcnt(3)
	v_pk_mul_f32 v[12:13], v[12:13], v[98:99]
	s_waitcnt lgkmcnt(2)
	v_pk_mul_f32 v[8:9], v[8:9], v[102:103]
	s_waitcnt lgkmcnt(1)
	v_pk_mul_f32 v[4:5], v[4:5], v[110:111]
	v_pk_mul_f32 v[14:15], v[14:15], v[100:101]
	v_pk_mul_f32 v[10:11], v[10:11], v[104:105]
	v_pk_mul_f32 v[6:7], v[6:7], v[112:113]
	s_waitcnt lgkmcnt(0)
	v_pk_mul_f32 v[2:3], v[2:3], v[116:117]
	v_pk_mul_f32 v[0:1], v[0:1], v[114:115]
	v_pk_mul_f32 v[60:61], v[60:61], v[98:99]
	v_pk_mul_f32 v[56:57], v[56:57], v[102:103]
	v_pk_mul_f32 v[52:53], v[52:53], v[110:111]
	v_pk_mul_f32 v[62:63], v[62:63], v[100:101]
	v_pk_mul_f32 v[58:59], v[58:59], v[104:105]
	v_pk_mul_f32 v[54:55], v[54:55], v[112:113]
	v_pk_mul_f32 v[50:51], v[50:51], v[116:117]
	v_pk_mul_f32 v[48:49], v[48:49], v[114:115]
	v_pk_mul_f32 v[44:45], v[44:45], v[98:99]
	v_pk_mul_f32 v[40:41], v[40:41], v[102:103]
	v_pk_mul_f32 v[36:37], v[36:37], v[110:111]
	v_pk_mul_f32 v[46:47], v[46:47], v[100:101]
	v_pk_mul_f32 v[42:43], v[42:43], v[104:105]
	v_pk_mul_f32 v[38:39], v[38:39], v[112:113]
	v_pk_mul_f32 v[34:35], v[34:35], v[116:117]
	v_pk_mul_f32 v[32:33], v[32:33], v[114:115]
	v_pk_mul_f32 v[28:29], v[28:29], v[98:99]
	v_pk_mul_f32 v[24:25], v[24:25], v[102:103]
	v_pk_mul_f32 v[20:21], v[20:21], v[110:111]
	v_pk_mul_f32 v[30:31], v[30:31], v[100:101]
	v_pk_mul_f32 v[26:27], v[26:27], v[104:105]
	v_pk_mul_f32 v[22:23], v[22:23], v[112:113]
	v_pk_mul_f32 v[18:19], v[18:19], v[116:117]
	v_pk_mul_f32 v[16:17], v[16:17], v[114:115]
.LBB0_447:
	v_cndmask_b32_e64 v97, v97, v175, s[8:9]
	v_mul_f32_e32 v97, 0xbe0293ee, v97
	v_fmamk_f32 v80, v80, 0x3e0293ee, v97
	v_fmamk_f32 v81, v81, 0x3e0293ee, v97
	v_fmamk_f32 v106, v93, 0x3e0293ee, v97
	v_fmamk_f32 v93, v74, 0x3e0293ee, v97
	v_exp_f32_e32 v74, v80
	v_fmamk_f32 v82, v82, 0x3e0293ee, v97
	v_fmamk_f32 v107, v94, 0x3e0293ee, v97
	v_fmamk_f32 v94, v75, 0x3e0293ee, v97
	v_exp_f32_e32 v75, v81
	v_fmamk_f32 v83, v83, 0x3e0293ee, v97
	v_fmamk_f32 v110, v95, 0x3e0293ee, v97
	v_fmamk_f32 v95, v76, 0x3e0293ee, v97
	v_exp_f32_e32 v76, v82
	v_fmamk_f32 v84, v84, 0x3e0293ee, v97
	v_fmamk_f32 v64, v64, 0x3e0293ee, v97
	v_exp_f32_e32 v80, v83
	v_fmamk_f32 v98, v85, 0x3e0293ee, v97
	v_fmamk_f32 v99, v86, 0x3e0293ee, v97
	v_fmamk_f32 v100, v87, 0x3e0293ee, v97
	v_fmamk_f32 v101, v88, 0x3e0293ee, v97
	v_fmamk_f32 v102, v89, 0x3e0293ee, v97
	v_fmamk_f32 v103, v90, 0x3e0293ee, v97
	v_fmamk_f32 v104, v91, 0x3e0293ee, v97
	v_fmamk_f32 v105, v92, 0x3e0293ee, v97
	v_fmamk_f32 v65, v65, 0x3e0293ee, v97
	v_fmamk_f32 v85, v66, 0x3e0293ee, v97
	v_fmamk_f32 v86, v67, 0x3e0293ee, v97
	v_fmamk_f32 v87, v68, 0x3e0293ee, v97
	v_fmamk_f32 v88, v69, 0x3e0293ee, v97
	v_fmamk_f32 v89, v70, 0x3e0293ee, v97
	v_fmamk_f32 v90, v71, 0x3e0293ee, v97
	v_fmamk_f32 v91, v72, 0x3e0293ee, v97
	v_fmamk_f32 v92, v73, 0x3e0293ee, v97
	v_exp_f32_e32 v81, v84
	v_fmamk_f32 v77, v77, 0x3e0293ee, v97
	v_fmamk_f32 v78, v78, 0x3e0293ee, v97
	v_fmac_f32_e32 v97, 0x3e0293ee, v79
	v_exp_f32_e32 v79, v64
	v_add_f32_e32 v64, 0, v74
	v_exp_f32_e32 v82, v98
	v_add_f32_e32 v64, v75, v64
	v_exp_f32_e32 v83, v99
	v_add_f32_e32 v64, v76, v64
	v_exp_f32_e32 v84, v100
	v_add_f32_e32 v64, v80, v64
	v_exp_f32_e32 v66, v101
	v_add_f32_e32 v64, v81, v64
	v_exp_f32_e32 v67, v102
	v_add_f32_e32 v64, v82, v64
	v_exp_f32_e32 v68, v103
	v_add_f32_e32 v64, v83, v64
	v_exp_f32_e32 v69, v104
	v_add_f32_e32 v64, v84, v64
	v_exp_f32_e32 v70, v105
	v_add_f32_e32 v64, v66, v64
	v_exp_f32_e32 v71, v106
	v_add_f32_e32 v64, v67, v64
	v_exp_f32_e32 v72, v107
	v_add_f32_e32 v64, v68, v64
	v_exp_f32_e32 v73, v110
	v_add_f32_e32 v64, v69, v64
	v_add_f32_e32 v64, v70, v64
	v_exp_f32_e32 v98, v65
	v_add_f32_e32 v64, v71, v64
	v_exp_f32_e32 v85, v85
	v_add_f32_e32 v64, v72, v64
	v_exp_f32_e32 v86, v86
	v_add_f32_e32 v64, v73, v64
	v_exp_f32_e32 v87, v87
	v_add_f32_e32 v64, v79, v64
	v_exp_f32_e32 v88, v88
	v_add_f32_e32 v64, v98, v64
	v_exp_f32_e32 v89, v89
	v_add_f32_e32 v64, v85, v64
	v_exp_f32_e32 v90, v90
	v_add_f32_e32 v64, v86, v64
	v_exp_f32_e32 v91, v91
	v_add_f32_e32 v64, v87, v64
	v_exp_f32_e32 v92, v92
	v_add_f32_e32 v64, v88, v64
	v_exp_f32_e32 v93, v93
	v_add_f32_e32 v64, v89, v64
	v_exp_f32_e32 v94, v94
	v_add_f32_e32 v64, v90, v64
	v_exp_f32_e32 v95, v95
	v_add_f32_e32 v64, v91, v64
	v_exp_f32_e32 v99, v77
	v_add_f32_e32 v64, v92, v64
	v_exp_f32_e32 v100, v78
	v_add_f32_e32 v64, v93, v64
	v_exp_f32_e32 v97, v97
	v_add_f32_e32 v64, v94, v64
	v_add_f32_e32 v64, v95, v64
	v_add_f32_e32 v64, v99, v64
	v_add_f32_e32 v64, v100, v64
	v_add_f32_e32 v64, v97, v64
	v_mov_b32_e32 v65, v64
	s_nop 1
	v_permlane32_swap_b32_e32 v64, v65
	v_cvt_pk_bf16_f32 v74, v74, v75
	v_cvt_pk_bf16_f32 v75, v76, v80
	v_cvt_pk_bf16_f32 v76, v81, v82
	v_cvt_pk_bf16_f32 v77, v83, v84
	v_cvt_pk_bf16_f32 v66, v66, v67
	v_cvt_pk_bf16_f32 v67, v68, v69
	v_cvt_pk_bf16_f32 v68, v70, v71
	v_cvt_pk_bf16_f32 v69, v72, v73
	v_cvt_pk_bf16_f32 v70, v79, v98
	v_cvt_pk_bf16_f32 v71, v85, v86
	v_cvt_pk_bf16_f32 v72, v87, v88
	v_cvt_pk_bf16_f32 v73, v89, v90
	v_cvt_pk_bf16_f32 v78, v91, v92
	v_cvt_pk_bf16_f32 v79, v93, v94
	v_cvt_pk_bf16_f32 v80, v95, v99
	v_cvt_pk_bf16_f32 v81, v100, v97
	ds_read_b64_tr_b16 v[82:83], v160 offset:0
	ds_read_b64_tr_b16 v[84:85], v160 offset:0x800
	ds_read_b64_tr_b16 v[86:87], v160 offset:0x1000
	ds_read_b64_tr_b16 v[88:89], v160 offset:0x1800
	ds_read_b64_tr_b16 v[90:91], v160 offset:0x2000
	ds_read_b64_tr_b16 v[92:93], v160 offset:0x2800
	ds_read_b64_tr_b16 v[98:99], v160 offset:0x3000
	ds_read_b64_tr_b16 v[100:101], v160 offset:0x3800
	s_waitcnt lgkmcnt(0)
	s_nop 0
	v_mfma_f32_32x32x16_bf16 v[0:15], v[74:77], v[82:85], v[0:15]
	ds_read_b64_tr_b16 v[82:83], v160 offset:0x200
	ds_read_b64_tr_b16 v[84:85], v160 offset:0xa00
	v_mfma_f32_32x32x16_bf16 v[0:15], v[66:69], v[86:89], v[0:15]
	ds_read_b64_tr_b16 v[86:87], v160 offset:0x1200
	ds_read_b64_tr_b16 v[88:89], v160 offset:0x1a00
	v_mfma_f32_32x32x16_bf16 v[0:15], v[70:73], v[90:93], v[0:15]
	ds_read_b64_tr_b16 v[90:91], v160 offset:0x2200
	ds_read_b64_tr_b16 v[92:93], v160 offset:0x2a00
	ds_read_b64_tr_b16 v[102:103], v160 offset:0x3200
	ds_read_b64_tr_b16 v[104:105], v160 offset:0x3a00
	s_waitcnt lgkmcnt(0)
	v_mfma_f32_32x32x16_bf16 v[0:15], v[78:81], v[98:101], v[0:15]
	v_mfma_f32_32x32x16_bf16 v[48:63], v[74:77], v[82:85], v[48:63]
	ds_read_b64_tr_b16 v[82:83], v160 offset:0x400
	ds_read_b64_tr_b16 v[84:85], v160 offset:0xc00
	v_mfma_f32_32x32x16_bf16 v[48:63], v[66:69], v[86:89], v[48:63]
	ds_read_b64_tr_b16 v[86:87], v160 offset:0x1400
	ds_read_b64_tr_b16 v[88:89], v160 offset:0x1c00
	v_mfma_f32_32x32x16_bf16 v[48:63], v[70:73], v[90:93], v[48:63]
	ds_read_b64_tr_b16 v[90:91], v160 offset:0x2400
	ds_read_b64_tr_b16 v[92:93], v160 offset:0x2c00
	ds_read_b64_tr_b16 v[98:99], v160 offset:0x3400
	ds_read_b64_tr_b16 v[100:101], v160 offset:0x3c00
	s_waitcnt lgkmcnt(0)
	v_mfma_f32_32x32x16_bf16 v[48:63], v[78:81], v[102:105], v[48:63]
	v_mfma_f32_32x32x16_bf16 v[32:47], v[74:77], v[82:85], v[32:47]
	ds_read_b64_tr_b16 v[82:83], v160 offset:0x600
	ds_read_b64_tr_b16 v[84:85], v160 offset:0xe00
	v_mfma_f32_32x32x16_bf16 v[32:47], v[66:69], v[86:89], v[32:47]
	ds_read_b64_tr_b16 v[86:87], v160 offset:0x1600
	ds_read_b64_tr_b16 v[88:89], v160 offset:0x1e00
	v_mfma_f32_32x32x16_bf16 v[32:47], v[70:73], v[90:93], v[32:47]
	ds_read_b64_tr_b16 v[90:91], v160 offset:0x2600
	ds_read_b64_tr_b16 v[92:93], v160 offset:0x2e00
	ds_read_b64_tr_b16 v[102:103], v160 offset:0x3600
	ds_read_b64_tr_b16 v[104:105], v160 offset:0x3e00
	s_waitcnt lgkmcnt(0)
	v_mfma_f32_32x32x16_bf16 v[32:47], v[78:81], v[98:101], v[32:47]
	v_mfma_f32_32x32x16_bf16 v[16:31], v[74:77], v[82:85], v[16:31]
	v_mfma_f32_32x32x16_bf16 v[16:31], v[66:69], v[86:89], v[16:31]
	v_mfma_f32_32x32x16_bf16 v[16:31], v[70:73], v[90:93], v[16:31]
	v_mfma_f32_32x32x16_bf16 v[16:31], v[78:81], v[102:105], v[16:31]
	s_and_saveexec_b64 s[2:3], s[6:7]
	s_cbranch_execz .LBB0_431
	v_add_f32_e32 v66, v108, v109
	v_fmac_f32_e32 v66, v159, v177
	v_add_f32_e32 v64, v64, v65
	v_fmac_f32_e32 v64, v66, v96
	ds_write_b32 v158, v64
	s_branch .LBB0_431
